# grid barrier: extra early L2 write-back (buffer_wbl2) issued by every 8th arriving workgroup of an XCD, so the XCD leader's final write-back finds little dirty data; stacked on early invalidate + GEMM
# baseline (speedup 1.0000x reference)
.LBB0_60:
	s_or_b64 exec, exec, s[6:7]
	v_cvt_f32_u32_e32 v4, v2
	s_waitcnt vmcnt(0)
	v_readfirstlane_b32 s4, v3
	v_sub_u32_e32 v3, 0, v2
	v_rcp_iflag_f32_e32 v4, v4
	v_add_u32_e32 v5, s4, v1
	v_mul_f32_e32 v4, 0x4f7ffffe, v4
	v_cvt_u32_f32_e32 v4, v4
	v_mul_lo_u32 v1, v3, v4
	v_mul_hi_u32 v1, v4, v1
	v_add_u32_e32 v1, v4, v1
	v_mul_hi_u32 v1, v5, v1
	v_mul_lo_u32 v3, v1, v2
	v_sub_u32_e32 v3, v5, v3
	v_add_u32_e32 v4, 1, v1
	v_cmp_ge_u32_e32 vcc, v3, v2
	s_nop 1
	v_cndmask_b32_e32 v1, v1, v4, vcc
	v_sub_u32_e32 v4, v3, v2
	v_cndmask_b32_e32 v3, v3, v4, vcc
	v_add_u32_e32 v4, 1, v1
	v_cmp_ge_u32_e32 vcc, v3, v2
	v_add_u32_e32 v3, 1, v5
	s_nop 0
	v_cndmask_b32_e32 v1, v1, v4, vcc
	v_mul_lo_u32 v4, v2, v1
	v_add_u32_e32 v2, v4, v2
	v_cmp_ne_u32_e32 vcc, v3, v2
	s_and_saveexec_b64 s[4:5], vcc
	s_xor_b64 s[4:5], exec, s[4:5]
	s_cbranch_execz .LBB0_74
	s_waitcnt lgkmcnt(0)
	v_mov_b32_e32 v0, 0x2000
	v_and_b32_e32 v4, 7, v5
	v_cmp_eq_u32_e32 vcc, 0, v4
	s_cbranch_vccz .Lewb_0
	buffer_wbl2 sc1
.Lewb_0:
	buffer_inv sc1
	global_load_dword v0, v0, s[2:3] offset:1024 sc1
	s_add_u32 s10, s2, 0x2400
	s_addc_u32 s11, s3, 0
	s_waitcnt vmcnt(0)
	v_cmp_eq_u32_e32 vcc, v0, v1
	s_and_saveexec_b64 s[6:7], vcc
	s_cbranch_execz .LBB0_73
	s_add_u32 s8, s90, 0x4200
	s_addc_u32 s9, s91, 0
	s_mov_b32 s19, 1
	s_mov_b64 s[12:13], 0
	v_mov_b32_e32 v0, 0
	s_branch .LBB0_64

.Lewb_7:
	buffer_inv sc1
	global_load_dword v0, v0, s[2:3] offset:1024 sc1
	s_add_u32 s14, s2, 0x2400
	s_addc_u32 s15, s3, 0
	s_waitcnt vmcnt(0)
	v_cmp_eq_u32_e32 vcc, v0, v1
	s_and_saveexec_b64 s[6:7], vcc
	s_cbranch_execz .LBB0_911
	s_add_u32 s8, s90, 0x4200
	s_addc_u32 s9, s91, 0
	s_mov_b32 s33, 1
	s_mov_b64 s[28:29], 0
	v_mov_b32_e32 v0, 0
	s_branch .LBB0_902

.Lewb_8:
	buffer_inv sc1
	global_load_dword v0, v0, s[2:3] offset:1024 sc1
	s_add_u32 s10, s2, 0x2400
	s_addc_u32 s11, s3, 0
	s_waitcnt vmcnt(0)
	v_cmp_eq_u32_e32 vcc, v0, v1
	s_and_saveexec_b64 s[6:7], vcc
	s_cbranch_execz .LBB0_1083
	s_add_u32 s8, s90, 0x4200
	s_addc_u32 s9, s91, 0
	s_mov_b32 s19, 1
	s_mov_b64 s[14:15], 0
	v_mov_b32_e32 v0, 0
	s_branch .LBB0_1074
